# adds: register-only w_up transpose in P3 (no LDS/barriers), de-serialized gla_sample and sgu_sample item loads, pipelined PB conversion
# speedup vs baseline: 1.0327x; 1.0074x over previous
; __device__ __forceinline__ float bf2f(unsigned b) { return __uint_as_float(b << 16); }
; __device__ __forceinline__ float logsig(float x) { return fminf(x, 0.f) - __logf(1.f + __expf(-fabsf(x))); }
; __device__ __forceinline__ void gla_sample_item(int nh, const u16* PROJ, u16* MIXIN, const float* wgate, const float* bgate, const float* ggla, const float* state_in, float* state_out, LAS unsigned char* lds) {
;     ...
;     if (tid < 256) {
;         const int t = tid >> 6, d = tid & 63;
;         const u16* pr = PROJ + ((size_t)TP + n * 4 + t) * NPROJ;
;         const u32x4 ga = *(const u32x4*)(pr + C_GLR), gb = *(const u32x4*)(pr + C_GLR + 8);
;         const float* wgp = wgate + h * 64 + d;
;         float logit = bgate[h * 64 + d];
;         logit += bf2f(ga.x & 0xffffu) * wgp[0] + bf2f(ga.x >> 16) * wgp[256] + bf2f(ga.y & 0xffffu) * wgp[512] + bf2f(ga.y >> 16) * wgp[768];
;         logit += bf2f(ga.z & 0xffffu) * wgp[1024] + bf2f(ga.z >> 16) * wgp[1280] + bf2f(ga.w & 0xffffu) * wgp[1536] + bf2f(ga.w >> 16) * wgp[1792];
;         logit += bf2f(gb.x & 0xffffu) * wgp[2048] + bf2f(gb.x >> 16) * wgp[2304] + bf2f(gb.y & 0xffffu) * wgp[2560] + bf2f(gb.y >> 16) * wgp[2816];
;         logit += bf2f(gb.z & 0xffffu) * wgp[3072] + bf2f(gb.z >> 16) * wgp[3328] + bf2f(gb.w & 0xffffu) * wgp[3584] + bf2f(gb.w >> 16) * wgp[3840];
;         AKQ[(t * 3 + 0) * 64 + d] = __expf(logsig(logit) * (1.f / 16.f));
;         AKQ[(t * 3 + 1) * 64 + d] = bf2f(pr[C_K + h * 64 + d]);
;         AKQ[(t * 3 + 2) * 64 + d] = bf2f(pr[C_Q + h * 64 + d]) * 0.125f;
;     }
.LBB0_224:
	s_cmpk_gt_i32 s50, 0x1ff
	s_mov_b64 s[78:79], -1
	s_cbranch_scc0 .LBB0_235
	s_cmpk_gt_u32 s50, 0x5ff
	s_cbranch_scc0 .LBB0_231
	v_readfirstlane_b32 s86, v67
	s_ashr_i32 s84, s86, 1
	s_add_i32 s35, s50, 0xfffffa00
	s_lshl_b32 s54, s84, 4
	s_and_b32 s85, s50, 0x1fc
	s_lshl_b32 s6, s35, 6
	s_ashr_i32 s55, s54, 31
	s_add_u32 s80, s54, s6
	s_addc_u32 s81, s55, 0
	s_lshl_b64 s[56:57], s[80:81], 9
	v_lshl_add_u64 v[0:1], v[54:55], 0, s[56:57]
	global_load_dword v21, v[0:1], off
	global_load_dword v20, v[0:1], off offset:512
	global_load_dword v19, v[0:1], off offset:1024
	global_load_dword v18, v[0:1], off offset:1536
	global_load_dword v17, v[0:1], off offset:2048
	global_load_dword v16, v[0:1], off offset:2560
	global_load_dword v14, v[0:1], off offset:3072
	global_load_dword v12, v[0:1], off offset:3584
	v_add_co_u32_e32 v0, vcc, 0x1000, v0
	s_and_b32 s55, s50, 3
	s_nop 0
	v_addc_co_u32_e32 v1, vcc, 0, v1, vcc
	global_load_dword v15, v[0:1], off
	global_load_dword v13, v[0:1], off offset:512
	global_load_dword v11, v[0:1], off offset:1024
	global_load_dword v10, v[0:1], off offset:1536
	global_load_dword v9, v[0:1], off offset:2048
	global_load_dword v8, v[0:1], off offset:2560
	global_load_dword v7, v[0:1], off offset:3072
	global_load_dword v6, v[0:1], off offset:3584
	s_mov_b64 s[82:83], exec
	v_readlane_b32 s56, v237, 16
	v_readlane_b32 s57, v237, 17
	s_and_b64 s[56:57], s[82:83], s[56:57]
	s_mov_b64 exec, s[56:57]
	s_cbranch_execz .LBB0_228
	v_or_b32_e32 v0, s85, v67
	v_mul_u32_u24_e32 v0, 0xb00, v0
	v_lshlrev_b32_e32 v52, 1, v0
	v_lshl_add_u64 v[4:5], s[4:5], 0, v[52:53]
	s_mov_b64 s[56:57], 0x5800c00
	v_add_co_u32_e32 v2, vcc, 0x5800000, v4
	s_lshl_b32 s6, s55, 8
	v_lshl_add_u64 v[0:1], v[4:5], 0, s[56:57]
	v_addc_co_u32_e32 v3, vcc, 0, v5, vcc
	v_lshl_add_u64 v[26:27], v[56:57], 0, s[6:7]
	global_load_dwordx4 v[22:25], v[2:3], off offset:3072
	s_nop 0
	global_load_dwordx4 v[0:3], v[0:1], off offset:16
	v_lshl_or_b32 v30, s55, 6, v128
	global_load_dword v170, v[26:27], off
	global_load_dword v171, v[26:27], off offset:1024
	global_load_dword v172, v[26:27], off offset:2048
	global_load_dword v173, v[26:27], off offset:3072
	v_add_co_u32_e32 v28, vcc, 0x1000, v26
	v_lshlrev_b32_e32 v31, 2, v30
	s_nop 0
	v_addc_co_u32_e32 v29, vcc, 0, v27, vcc
	global_load_dword v174, v[28:29], off
	global_load_dword v175, v[28:29], off offset:1024
	global_load_dword v176, v[28:29], off offset:2048
	global_load_dword v177, v[28:29], off offset:3072
	v_add_co_u32_e32 v28, vcc, 0x2000, v26
	s_nop 1
	v_addc_co_u32_e32 v29, vcc, 0, v27, vcc
	global_load_dword v178, v[28:29], off
	global_load_dword v179, v[28:29], off offset:1024
	global_load_dword v180, v[28:29], off offset:2048
	global_load_dword v181, v[28:29], off offset:3072
	v_add_co_u32_e32 v28, vcc, 0x3000, v26
	s_nop 1
	v_addc_co_u32_e32 v29, vcc, 0, v27, vcc
	global_load_dword v182, v[28:29], off
	global_load_dword v183, v[28:29], off offset:1024
	global_load_dword v184, v[28:29], off offset:2048
	global_load_dword v185, v[28:29], off offset:3072
	global_load_dword v186, v31, s[38:39]
	v_lshlrev_b32_e32 v52, 1, v30
	s_mov_b64 s[56:57], 0x5800000
	v_lshl_add_u64 v[28:29], v[4:5], 0, v[52:53]
	v_lshl_add_u64 v[188:189], v[28:29], 0, s[56:57]
	global_load_ushort v190, v[188:189], off offset:512
	global_load_ushort v191, v[188:189], off
	s_movk_i32 s6, 0x3000
	s_waitcnt vmcnt(0)
	v_lshlrev_b32_e32 v29, 16, v22
	v_and_b32_e32 v22, 0xffff0000, v22
	v_mul_f32_e32 v22, v171, v22
	v_fmac_f32_e32 v22, v170, v29
	v_lshlrev_b32_e32 v29, 16, v23
	v_and_b32_e32 v23, 0xffff0000, v23
	v_fmac_f32_e32 v22, v172, v29
	v_fmac_f32_e32 v22, v173, v23
	v_add_f32_e32 v31, v186, v22
	v_lshlrev_b32_e32 v52, 16, v24
	v_and_b32_e32 v24, 0xffff0000, v24
	v_mul_f32_e32 v24, v175, v24
	v_fmac_f32_e32 v24, v174, v52
	v_lshlrev_b32_e32 v52, 16, v25
	v_and_b32_e32 v25, 0xffff0000, v25
	v_fmac_f32_e32 v24, v176, v52
	v_fmac_f32_e32 v24, v177, v25
	v_add_f32_e32 v22, v31, v24
	v_lshlrev_b32_e32 v23, 16, v0
	v_and_b32_e32 v0, 0xffff0000, v0
	v_mul_f32_e32 v0, v179, v0
	v_fmac_f32_e32 v0, v178, v23
	v_lshlrev_b32_e32 v23, 16, v1
	v_and_b32_e32 v1, 0xffff0000, v1
	v_fmac_f32_e32 v0, v180, v23
	v_fmac_f32_e32 v0, v181, v1
	v_add_f32_e32 v22, v22, v0
	v_lshlrev_b32_e32 v23, 16, v2
	v_and_b32_e32 v2, 0xffff0000, v2
	v_mul_f32_e32 v2, v183, v2
	v_fmac_f32_e32 v2, v182, v23
	v_lshlrev_b32_e32 v23, 16, v3
	v_and_b32_e32 v3, 0xffff0000, v3
	v_fmac_f32_e32 v2, v184, v23
	v_fmac_f32_e32 v2, v185, v3
	v_add_f32_e32 v0, v22, v2
	v_min_f32_e32 v1, 0, v0
	v_mul_f32_e64 v0, |v0|, s20
	v_exp_f32_e32 v0, v0
	s_nop 0
	v_add_f32_e32 v0, 1.0, v0
	v_cmp_gt_f32_e32 vcc, s21, v0
	s_nop 1
	v_cndmask_b32_e64 v2, 0, 32, vcc
	v_ldexp_f32 v0, v0, v2
	v_log_f32_e32 v0, v0
	s_nop 0
	v_mul_f32_e32 v2, 0x3f317217, v0
	v_fma_f32 v2, v0, s8, -v2
	v_fmac_f32_e32 v2, 0x3377d1cf, v0
	v_fmac_f32_e32 v2, 0x3f317217, v0
	v_cmp_lt_f32_e64 s[78:79], |v0|, s9
	s_nop 1
	v_cndmask_b32_e64 v0, v0, v2, s[78:79]
	v_cndmask_b32_e32 v2, 0, v152, vcc
	v_sub_f32_e32 v0, v0, v2
	v_sub_f32_e32 v0, v1, v0
	v_mul_f32_e32 v0, 0x3d800000, v0
	v_mul_f32_e32 v0, 0x3fb8aa3b, v0
	v_exp_f32_e32 v22, v0
	v_lshlrev_b32_e32 v2, 16, v190
	ds_write2st64_b32 v71, v22, v2 offset1:1
	v_lshlrev_b32_e32 v0, 16, v191
	v_mul_f32_e32 v0, 0x3e000000, v0
	ds_write_b32 v71, v0 offset:512
; #define LAS __attribute__((address_space(3)))
; __device__ __forceinline__ float bf2f(unsigned b) { return __uint_as_float(b << 16); }
; #define LBAR() do { asm volatile("s_waitcnt lgkmcnt(0)" ::: "memory"); __builtin_amdgcn_s_barrier(); asm volatile("" ::: "memory"); } while (0)
; __device__ __forceinline__ void gla_sample_item(int nh, const u16* PROJ, u16* MIXIN, const float* wgate, const float* bgate, const float* ggla, const float* state_in, float* state_out, LAS unsigned char* lds) {
;     ...
;     LBAR();
; #pragma unroll
;     for (int t = 0; t < 4; ++t) {
;         const float v = bf2f(PROJ[((size_t)TP + n * 4 + t) * NPROJ + C_V + h * 128 + e]);
;         float po = 0.f;
; #pragma unroll
;         for (int i4 = 0; i4 < 4; ++i4) {
;             const f32x4 a = *(const LAS f32x4*)(AKQ + (t * 3 + 0) * 64 + dq * 16 + 4 * i4), k = *(const LAS f32x4*)(AKQ + (t * 3 + 1) * 64 + dq * 16 + 4 * i4), q = *(const LAS f32x4*)(AKQ + (t * 3 + 2) * 64 + dq * 16 + 4 * i4);
;             S[4 * i4 + 0] = a.x * S[4 * i4 + 0] + k.x * v; po += q.x * S[4 * i4 + 0];
;             S[4 * i4 + 1] = a.y * S[4 * i4 + 1] + k.y * v; po += q.y * S[4 * i4 + 1];
;             S[4 * i4 + 2] = a.z * S[4 * i4 + 2] + k.z * v; po += q.z * S[4 * i4 + 2];
;             S[4 * i4 + 3] = a.w * S[4 * i4 + 3] + k.w * v; po += q.w * S[4 * i4 + 3];
;         }
;         PO[(t * 4 + dq) * 128 + e] = po;
;     }
.LBB0_228:
	s_or_b64 exec, exec, s[82:83]
	s_lshl_b32 s6, s55, 7
	v_or_b32_e32 v2, s6, v142
	s_mul_i32 s55, s85, 0xb00
	v_or_b32_e32 v0, s55, v2
	s_waitcnt lgkmcnt(0)
	s_barrier
	v_lshlrev_b32_e32 v52, 1, v0
	global_load_ushort v3, v52, s[4:5]
	v_lshl_add_u64 v[192:193], s[4:5], 0, v[52:53]
	v_add_co_u32_e32 v194, vcc, 0x1000, v192
	s_nop 1
	v_addc_co_u32_e32 v195, vcc, 0, v193, vcc
	global_load_ushort v196, v[194:195], off offset:1536
	v_add_co_u32_e32 v194, vcc, 0x2000, v192
	s_nop 1
	v_addc_co_u32_e32 v195, vcc, 0, v193, vcc
	global_load_ushort v197, v[194:195], off offset:3072
	v_add_co_u32_e32 v194, vcc, 0x4000, v192
	s_nop 1
	v_addc_co_u32_e32 v195, vcc, 0, v193, vcc
	global_load_ushort v198, v[194:195], off offset:512
	s_lshl_b32 s54, s54, 2
	s_add_i32 s54, s54, 0
	v_mov_b32_e32 v5, s54
	ds_read_b128 v[22:25], v5 offset:256
	ds_read_b128 v[26:29], v5 offset:512
	ds_read_b128 v[88:91], v5
	ds_read_b128 v[92:95], v5 offset:16
	ds_read_b128 v[96:99], v5 offset:32
	ds_read_b128 v[100:103], v5 offset:48
	v_lshl_add_u64 v[0:1], s[4:5], 0, v[52:53]
	v_lshl_add_u32 v4, s84, 9, v106
	s_movk_i32 s54, 0x2000
	s_or_b32 s35, s35, 3
	s_mulk_i32 s35, 0xb00
	s_lshl_b64 s[78:79], s[80:81], 7
	s_waitcnt vmcnt(0)
	v_lshlrev_b32_e32 v3, 16, v3
	s_waitcnt lgkmcnt(5)
	v_mul_f32_e32 v30, v22, v3
	v_mul_f32_e32 v31, v23, v3
	v_mul_f32_e32 v52, v24, v3
	v_mul_f32_e32 v79, v25, v3
	s_waitcnt lgkmcnt(3)
	v_fmac_f32_e32 v30, v21, v88
	v_fmac_f32_e32 v31, v20, v89
	v_fmac_f32_e32 v52, v19, v90
	v_fmac_f32_e32 v79, v18, v91
	ds_read_b128 v[18:21], v5 offset:272
	ds_read_b128 v[22:25], v5 offset:528
	v_fma_f32 v26, v26, v30, 0
	v_fmac_f32_e32 v26, v27, v31
	v_fmac_f32_e32 v26, v28, v52
	s_waitcnt lgkmcnt(1)
	v_mul_f32_e32 v81, v18, v3
	v_fmac_f32_e32 v26, v29, v79
	v_fmac_f32_e32 v81, v17, v92
	v_mul_f32_e32 v83, v19, v3
	s_waitcnt lgkmcnt(0)
	v_fmac_f32_e32 v26, v22, v81
	v_fmac_f32_e32 v83, v16, v93
	v_fmac_f32_e32 v26, v23, v83
	v_mul_f32_e32 v85, v20, v3
	v_mul_f32_e32 v87, v21, v3
	ds_read_b128 v[16:19], v5 offset:288
	ds_read_b128 v[20:23], v5 offset:544
	v_fmac_f32_e32 v85, v14, v94
	v_fmac_f32_e32 v87, v12, v95
	v_fmac_f32_e32 v26, v24, v85
	s_waitcnt lgkmcnt(1)
	v_mul_f32_e32 v88, v16, v3
	v_mul_f32_e32 v89, v17, v3
	v_mul_f32_e32 v90, v18, v3
	v_mul_f32_e32 v91, v19, v3
	v_fmac_f32_e32 v88, v15, v96
	v_fmac_f32_e32 v89, v13, v97
	v_fmac_f32_e32 v90, v11, v98
	v_fmac_f32_e32 v91, v10, v99
	ds_read_b128 v[10:13], v5 offset:304
	ds_read_b128 v[14:17], v5 offset:560
	v_fmac_f32_e32 v26, v25, v87
	s_waitcnt lgkmcnt(2)
	v_fmac_f32_e32 v26, v20, v88
	v_fmac_f32_e32 v26, v21, v89
	s_waitcnt lgkmcnt(1)
	v_mul_f32_e32 v92, v10, v3
	v_mul_f32_e32 v93, v11, v3
	v_mul_f32_e32 v94, v12, v3
	v_mul_f32_e32 v3, v13, v3
	v_fmac_f32_e32 v3, v6, v103
	v_add_co_u32_e32 v6, vcc, s3, v0
	v_fmac_f32_e32 v94, v7, v102
	s_nop 0
	v_addc_co_u32_e32 v7, vcc, 0, v1, vcc
	s_nop 0
	v_fmac_f32_e32 v26, v22, v90
	v_fmac_f32_e32 v26, v23, v91
	v_fmac_f32_e32 v92, v9, v100
	s_waitcnt lgkmcnt(0)
	v_fmac_f32_e32 v26, v14, v92
	v_fmac_f32_e32 v93, v8, v101
	v_fmac_f32_e32 v26, v15, v93
	v_fmac_f32_e32 v26, v16, v94
	v_fmac_f32_e32 v26, v17, v3
	ds_write_b32 v4, v26 offset:3072
	v_add_co_u32_e32 v0, vcc, s54, v0
	s_nop 0
	v_lshlrev_b32_e32 v95, 16, v196
	ds_read_b128 v[6:9], v5 offset:1024
	ds_read_b128 v[10:13], v5 offset:1280
	ds_read_b128 v[14:17], v5 offset:768
	ds_read_b128 v[18:21], v5 offset:784
	ds_read_b128 v[22:25], v5 offset:800
	ds_read_b128 v[26:29], v5 offset:816
	s_waitcnt lgkmcnt(5)
	v_mul_f32_e32 v96, v6, v95
	s_waitcnt lgkmcnt(3)
	v_fmac_f32_e32 v96, v30, v14
	v_mul_f32_e32 v30, v7, v95
	v_fma_f32 v14, v10, v96, 0
	v_fmac_f32_e32 v30, v31, v15
	v_mul_f32_e32 v31, v8, v95
	v_fmac_f32_e32 v14, v11, v30
	v_fmac_f32_e32 v31, v52, v16
	v_mul_f32_e32 v52, v9, v95
	v_fmac_f32_e32 v14, v12, v31
	v_fmac_f32_e32 v52, v79, v17
	v_fmac_f32_e32 v14, v13, v52
	ds_read_b128 v[6:9], v5 offset:1040
	ds_read_b128 v[10:13], v5 offset:1296
	v_addc_co_u32_e32 v1, vcc, 0, v1, vcc
	s_waitcnt lgkmcnt(1)
	v_mul_f32_e32 v79, v6, v95
	v_fmac_f32_e32 v79, v81, v18
	v_mul_f32_e32 v81, v7, v95
	s_waitcnt lgkmcnt(0)
	v_fmac_f32_e32 v14, v10, v79
	v_fmac_f32_e32 v81, v83, v19
	v_mul_f32_e32 v83, v8, v95
	v_fmac_f32_e32 v14, v11, v81
	v_fmac_f32_e32 v83, v85, v20
	v_mul_f32_e32 v85, v9, v95
	v_fmac_f32_e32 v14, v12, v83
	v_fmac_f32_e32 v85, v87, v21
	v_fmac_f32_e32 v14, v13, v85
	ds_read_b128 v[6:9], v5 offset:1056
	ds_read_b128 v[10:13], v5 offset:1312
	s_waitcnt lgkmcnt(1)
	v_mul_f32_e32 v87, v6, v95
	v_fmac_f32_e32 v87, v88, v22
	v_mul_f32_e32 v97, v7, v95
	s_waitcnt lgkmcnt(0)
	v_fmac_f32_e32 v14, v10, v87
	v_fmac_f32_e32 v97, v89, v23
	v_mul_f32_e32 v98, v8, v95
	v_fmac_f32_e32 v14, v11, v97
	v_fmac_f32_e32 v98, v90, v24
	v_mul_f32_e32 v99, v9, v95
	v_fmac_f32_e32 v14, v12, v98
	v_fmac_f32_e32 v99, v91, v25
	v_fmac_f32_e32 v14, v13, v99
	ds_read_b128 v[6:9], v5 offset:1072
	ds_read_b128 v[10:13], v5 offset:1328
	s_nop 0
	s_waitcnt lgkmcnt(1)
	v_mul_f32_e32 v100, v6, v95
	v_fmac_f32_e32 v100, v92, v26
	v_mul_f32_e32 v92, v7, v95
	s_waitcnt lgkmcnt(0)
	v_fmac_f32_e32 v14, v10, v100
	v_fmac_f32_e32 v92, v93, v27
	v_mul_f32_e32 v93, v8, v95
	v_fmac_f32_e32 v14, v11, v92
	v_fmac_f32_e32 v93, v94, v28
	v_mul_f32_e32 v94, v9, v95
	v_fmac_f32_e32 v14, v12, v93
	v_fmac_f32_e32 v94, v3, v29
	v_fmac_f32_e32 v14, v13, v94
	ds_write_b32 v4, v14 offset:5120
	ds_read_b128 v[6:9], v5 offset:1792
	ds_read_b128 v[10:13], v5 offset:2048
	ds_read_b128 v[14:17], v5 offset:1536
	ds_read_b128 v[22:25], v5 offset:1552
	ds_read_b128 v[26:29], v5 offset:1568
	ds_read_b128 v[88:91], v5 offset:1584
	s_nop 0
	v_lshlrev_b32_e32 v0, 16, v197
	s_waitcnt lgkmcnt(5)
; #define LAS __attribute__((address_space(3)))
; __device__ __forceinline__ float bf2f(unsigned b) { return __uint_as_float(b << 16); }
; #define LBAR() do { asm volatile("s_waitcnt lgkmcnt(0)" ::: "memory"); __builtin_amdgcn_s_barrier(); asm volatile("" ::: "memory"); } while (0)
; __device__ __forceinline__ void gla_sample_item(int nh, const u16* PROJ, u16* MIXIN, const float* wgate, const float* bgate, const float* ggla, const float* state_in, float* state_out, LAS unsigned char* lds) {
;     ...
; #pragma unroll
;     for (int t = 0; t < 4; ++t) {
;         const float v = bf2f(PROJ[((size_t)TP + n * 4 + t) * NPROJ + C_V + h * 128 + e]);
;         float po = 0.f;
; #pragma unroll
;         for (int i4 = 0; i4 < 4; ++i4) {
;             const f32x4 a = *(const LAS f32x4*)(AKQ + (t * 3 + 0) * 64 + dq * 16 + 4 * i4), k = *(const LAS f32x4*)(AKQ + (t * 3 + 1) * 64 + dq * 16 + 4 * i4), q = *(const LAS f32x4*)(AKQ + (t * 3 + 2) * 64 + dq * 16 + 4 * i4);
;             S[4 * i4 + 0] = a.x * S[4 * i4 + 0] + k.x * v; po += q.x * S[4 * i4 + 0];
;             S[4 * i4 + 1] = a.y * S[4 * i4 + 1] + k.y * v; po += q.y * S[4 * i4 + 1];
;             S[4 * i4 + 2] = a.z * S[4 * i4 + 2] + k.z * v; po += q.z * S[4 * i4 + 2];
;             S[4 * i4 + 3] = a.w * S[4 * i4 + 3] + k.w * v; po += q.w * S[4 * i4 + 3];
;         }
;         PO[(t * 4 + dq) * 128 + e] = po;
;     }
;     float* so = state_out + ((size_t)nh * 64 + dq * 16) * 128 + e;
; #pragma unroll
;     for (int i = 0; i < 16; ++i) so[i * 128] = S[i];
;     LBAR();
;     const int t2 = w >> 1, e2 = (w & 1) * 64 + lane;
;     const float o = (PO[(t2 * 4 + 0) * 128 + e2] + PO[(t2 * 4 + 1) * 128 + e2]) + (PO[(t2 * 4 + 2) * 128 + e2] + PO[(t2 * 4 + 3) * 128 + e2]);
;     const float part = wave_sum(o * o);
;     if (lane == 0) SS[w] = part;
;     LBAR();
;     const float rs = rsqrtf((SS[2 * t2] + SS[2 * t2 + 1]) * (1.f / 128.f) + EPS);
	v_mul_f32_e32 v18, v6, v0
	s_waitcnt lgkmcnt(3)
	v_fmac_f32_e32 v18, v96, v14
	v_mul_f32_e32 v19, v7, v0
	v_fma_f32 v1, v10, v18, 0
	v_fmac_f32_e32 v19, v30, v15
	v_mul_f32_e32 v20, v8, v0
	v_fmac_f32_e32 v1, v11, v19
	v_fmac_f32_e32 v20, v31, v16
	v_mul_f32_e32 v21, v9, v0
	v_fmac_f32_e32 v1, v12, v20
	v_fmac_f32_e32 v21, v52, v17
	v_fmac_f32_e32 v1, v13, v21
	ds_read_b128 v[6:9], v5 offset:1808
	ds_read_b128 v[10:13], v5 offset:2064
	v_add_u32_e32 v52, s35, v2
	s_lshl_b32 s35, s86, 6
	s_waitcnt lgkmcnt(1)
	v_mul_f32_e32 v17, v6, v0
	v_mul_f32_e32 v16, v7, v0
	v_mul_f32_e32 v15, v8, v0
	v_mul_f32_e32 v14, v9, v0
	v_fmac_f32_e32 v17, v79, v22
	v_fmac_f32_e32 v16, v81, v23
	v_fmac_f32_e32 v15, v83, v24
	v_fmac_f32_e32 v14, v85, v25
	ds_read_b128 v[6:9], v5 offset:1824
	ds_read_b128 v[22:25], v5 offset:2080
	s_waitcnt lgkmcnt(2)
	v_fmac_f32_e32 v1, v10, v17
	v_fmac_f32_e32 v1, v11, v16
	v_fmac_f32_e32 v1, v12, v15
	s_waitcnt lgkmcnt(1)
	v_mul_f32_e32 v10, v6, v0
	v_fmac_f32_e32 v1, v13, v14
	v_fmac_f32_e32 v10, v87, v26
	v_mul_f32_e32 v11, v7, v0
	s_waitcnt lgkmcnt(0)
	v_fmac_f32_e32 v1, v22, v10
	v_fmac_f32_e32 v11, v97, v27
	v_mul_f32_e32 v12, v8, v0
	v_fmac_f32_e32 v1, v23, v11
	v_fmac_f32_e32 v12, v98, v28
	v_mul_f32_e32 v13, v9, v0
	v_fmac_f32_e32 v1, v24, v12
	v_fmac_f32_e32 v13, v99, v29
	v_fmac_f32_e32 v1, v25, v13
	ds_read_b128 v[22:25], v5 offset:1840
	ds_read_b128 v[26:29], v5 offset:2096
	s_waitcnt lgkmcnt(1)
	v_mul_f32_e32 v9, v22, v0
	v_fmac_f32_e32 v9, v100, v88
	v_mul_f32_e32 v8, v23, v0
	s_waitcnt lgkmcnt(0)
	v_fmac_f32_e32 v1, v26, v9
	v_fmac_f32_e32 v8, v92, v89
	v_mul_f32_e32 v7, v24, v0
	v_fmac_f32_e32 v1, v27, v8
	v_fmac_f32_e32 v7, v93, v90
	v_mul_f32_e32 v6, v25, v0
	v_fmac_f32_e32 v1, v28, v7
	v_fmac_f32_e32 v6, v94, v91
	v_fmac_f32_e32 v1, v29, v6
	ds_write_b32 v4, v1 offset:7168
	v_lshl_add_u64 v[0:1], v[52:53], 1, s[4:5]
	s_nop 0
	s_nop 0
	v_lshlrev_b32_e32 v30, 16, v198
	ds_read_b128 v[22:25], v5 offset:2560
	ds_read_b128 v[26:29], v5 offset:2816
	ds_read_b128 v[88:91], v5 offset:2304
	ds_read_b128 v[92:95], v5 offset:2320
	ds_read_b128 v[96:99], v5 offset:2336
	ds_read_b128 v[0:3], v5 offset:2352
	s_waitcnt lgkmcnt(5)
	v_mul_f32_e32 v31, v22, v30
	s_waitcnt lgkmcnt(3)
	v_fmac_f32_e32 v31, v18, v88
	v_mul_f32_e32 v52, v23, v30
	v_fma_f32 v26, v26, v31, 0
	v_fmac_f32_e32 v52, v19, v89
	v_fmac_f32_e32 v26, v27, v52
	v_mul_f32_e32 v27, v24, v30
	v_fmac_f32_e32 v27, v20, v90
	v_fmac_f32_e32 v26, v28, v27
	v_mul_f32_e32 v28, v25, v30
	v_fmac_f32_e32 v28, v21, v91
	ds_read_b128 v[18:21], v5 offset:2576
	ds_read_b128 v[22:25], v5 offset:2832
	v_fmac_f32_e32 v26, v29, v28
	s_waitcnt lgkmcnt(1)
	v_mul_f32_e32 v29, v18, v30
	v_fmac_f32_e32 v29, v17, v92
	s_waitcnt lgkmcnt(0)
	v_fmac_f32_e32 v26, v22, v29
	v_mul_f32_e32 v22, v19, v30
	v_fmac_f32_e32 v22, v16, v93
	v_fmac_f32_e32 v26, v23, v22
	v_mul_f32_e32 v23, v20, v30
	v_fmac_f32_e32 v23, v15, v94
	v_fmac_f32_e32 v26, v24, v23
	v_mul_f32_e32 v24, v21, v30
	v_fmac_f32_e32 v24, v14, v95
	ds_read_b128 v[14:17], v5 offset:2592
	ds_read_b128 v[18:21], v5 offset:2848
	v_fmac_f32_e32 v26, v25, v24
	s_waitcnt lgkmcnt(1)
	v_mul_f32_e32 v25, v14, v30
	v_fmac_f32_e32 v25, v10, v96
	s_waitcnt lgkmcnt(0)
	v_fmac_f32_e32 v26, v18, v25
	v_mul_f32_e32 v18, v15, v30
	v_fmac_f32_e32 v18, v11, v97
	v_fmac_f32_e32 v26, v19, v18
	v_mul_f32_e32 v19, v16, v30
	v_fmac_f32_e32 v19, v12, v98
	v_fmac_f32_e32 v26, v20, v19
	v_mul_f32_e32 v20, v17, v30
	v_fmac_f32_e32 v20, v13, v99
	ds_read_b128 v[10:13], v5 offset:2608
	ds_read_b128 v[14:17], v5 offset:2864
	v_fmac_f32_e32 v26, v21, v20
	s_waitcnt lgkmcnt(1)
	v_mul_f32_e32 v5, v10, v30
	v_fmac_f32_e32 v5, v9, v0
	v_mul_f32_e32 v9, v11, v30
	s_waitcnt lgkmcnt(0)
	v_fmac_f32_e32 v26, v14, v5
	v_fmac_f32_e32 v9, v8, v1
	v_mul_f32_e32 v8, v12, v30
	v_fmac_f32_e32 v26, v15, v9
	v_fmac_f32_e32 v8, v7, v2
	v_mul_f32_e32 v2, v13, v30
	v_fmac_f32_e32 v26, v16, v8
	v_fmac_f32_e32 v2, v6, v3
	v_fmac_f32_e32 v26, v17, v2
	v_lshl_add_u64 v[0:1], s[78:79], 2, v[58:59]
	ds_write_b32 v4, v26 offset:9216
	global_store_dword v[0:1], v31, off
	global_store_dword v[0:1], v52, off offset:512
	global_store_dword v[0:1], v27, off offset:1024
	global_store_dword v[0:1], v28, off offset:1536
	global_store_dword v[0:1], v29, off offset:2048
	global_store_dword v[0:1], v22, off offset:2560
	global_store_dword v[0:1], v23, off offset:3072
	global_store_dword v[0:1], v24, off offset:3584
	v_add_co_u32_e32 v0, vcc, s3, v0
	s_nop 1
	v_addc_co_u32_e32 v1, vcc, 0, v1, vcc
	global_store_dword v[0:1], v25, off
	global_store_dword v[0:1], v18, off offset:512
	global_store_dword v[0:1], v19, off offset:1024
	global_store_dword v[0:1], v20, off offset:1536
	global_store_dword v[0:1], v5, off offset:2048
	global_store_dword v[0:1], v9, off offset:2560
	global_store_dword v[0:1], v8, off offset:3072
	global_store_dword v[0:1], v2, off offset:3584
	v_and_or_b32 v0, s35, 64, v128
	s_lshl_b32 s35, s84, 11
	s_add_i32 s35, s35, 0
	s_waitcnt lgkmcnt(0)
	s_barrier
	v_lshl_add_u32 v1, v0, 2, s35
	ds_read2st64_b32 v[2:3], v1 offset0:12 offset1:14
	s_waitcnt lgkmcnt(0)
	v_add_f32_e32 v4, v2, v3
	ds_read2st64_b32 v[2:3], v1 offset0:16 offset1:18
	s_waitcnt lgkmcnt(0)
	v_add_f32_e32 v1, v2, v3
	v_and_b32_e32 v3, 64, v153
	v_add_f32_e32 v1, v4, v1
	v_add_u32_e32 v3, 64, v3
	v_xor_b32_e32 v4, 1, v153
	v_cmp_lt_i32_e32 vcc, v4, v3
	v_mul_f32_e32 v2, v1, v1
	s_nop 0
	v_cndmask_b32_e32 v4, v153, v4, vcc
	v_lshlrev_b32_e32 v4, 2, v4
	ds_bpermute_b32 v2, v4, v2
	v_xor_b32_e32 v4, 2, v153
	v_cmp_lt_i32_e32 vcc, v4, v3
	s_waitcnt lgkmcnt(0)
	v_fmac_f32_e32 v2, v1, v1
	v_cndmask_b32_e32 v4, v153, v4, vcc
	v_lshlrev_b32_e32 v4, 2, v4
	ds_bpermute_b32 v4, v4, v2
	s_waitcnt lgkmcnt(0)
	v_add_f32_e32 v2, v2, v4
	v_xor_b32_e32 v4, 4, v153
	v_cmp_lt_i32_e32 vcc, v4, v3
	s_nop 1
	v_cndmask_b32_e32 v4, v153, v4, vcc
	v_lshlrev_b32_e32 v4, 2, v4
	ds_bpermute_b32 v4, v4, v2
	s_waitcnt lgkmcnt(0)
	v_add_f32_e32 v2, v2, v4
	v_xor_b32_e32 v4, 8, v153
	v_cmp_lt_i32_e32 vcc, v4, v3
	s_nop 1
	v_cndmask_b32_e32 v4, v153, v4, vcc
	v_lshlrev_b32_e32 v4, 2, v4
	ds_bpermute_b32 v4, v4, v2
	s_waitcnt lgkmcnt(0)
	v_add_f32_e32 v2, v2, v4
	v_xor_b32_e32 v4, 16, v153
	v_cmp_lt_i32_e32 vcc, v4, v3
	s_nop 1
	v_cndmask_b32_e32 v4, v153, v4, vcc
	v_lshlrev_b32_e32 v4, 2, v4
	ds_bpermute_b32 v4, v4, v2
	s_waitcnt lgkmcnt(0)
	v_add_f32_e32 v2, v2, v4
	v_xor_b32_e32 v4, 32, v153
	v_cmp_lt_i32_e32 vcc, v4, v3
	s_nop 1
	v_cndmask_b32_e32 v3, v153, v4, vcc
	v_lshlrev_b32_e32 v3, 2, v3
	ds_bpermute_b32 v3, v3, v2
	s_mov_b64 s[78:79], exec
	v_readlane_b32 s54, v237, 18
	v_readlane_b32 s55, v237, 19
	s_and_b64 s[54:55], s[78:79], s[54:55]
	s_mov_b64 exec, s[54:55]
	s_cbranch_execz .LBB0_230
	s_lshl_b32 s35, s86, 2
	s_add_i32 s35, s35, 0
	s_waitcnt lgkmcnt(0)
	v_add_f32_e32 v2, v2, v3
	v_mov_b32_e32 v3, s35
	ds_write_b32 v3, v2 offset:11264

; __device__ __forceinline__ float bf2f(unsigned b) { return __uint_as_float(b << 16); }
; __device__ __forceinline__ void sgu_sample_item(int item, const u16* PROJ, u16* MIXIN, const float* gln, const float* bln, const float* wsp, const float* bsp, float* vout, int lane) {
;     const int n = item >> 2, hh = item & 3; const int c0 = hh * 128 + 2 * lane;
;     const float g0 = gln[c0], g1 = gln[c0 + 1], b0 = bln[c0], b1 = bln[c0 + 1];
;     float vn0[4], vn1[4];
; #pragma unroll
;     for (int t = 0; t < 4; ++t) { const size_t row = (size_t)TP + n * 4 + t; const unsigned raw = *(const unsigned*)(PROJ + row * NPROJ + C_VS + c0);
;         const float x0 = bf2f(raw & 0xffffu), x1 = bf2f(raw >> 16);
;         const float mu = wave_sum(x0 + x1) * (1.f / 128.f), d0 = x0 - mu, d1 = x1 - mu;
;         const float rstd = rsqrtf(wave_sum(d0 * d0 + d1 * d1) * (1.f / 128.f) + EPS);
;         vn0[t] = d0 * rstd * g0 + b0; vn1[t] = d1 * rstd * g1 + b1;
;         *(f32x2*)(vout + ((size_t)n * 4 + t) * 512 + c0) = (f32x2){vn0[t], vn1[t]}; }
.LBB0_250:
	s_and_b32 s6, s49, -4
	s_ashr_i32 s42, s49, 2
	s_ashr_i32 s7, s6, 31
	s_add_u32 s30, s6, 0x4000
	s_addc_u32 s31, s7, 0
	s_ashr_i32 s43, s42, 31
	s_mul_hi_u32 s54, s30, 0x1600
	s_lshl_b64 s[50:51], s[42:43], 13
	s_mul_i32 s42, s31, 0x1600
	s_mul_i32 s55, s30, 0x1600
	s_add_i32 s54, s54, s42
	s_add_u32 s42, s4, s55
	s_addc_u32 s43, s5, s54
	v_lshl_add_u64 v[14:15], s[42:43], 0, v[0:1]
	v_add_co_u32_e32 v10, vcc, s3, v14
	v_lshl_add_u64 v[52:53], v[6:7], 0, s[50:51]
	s_nop 0
	v_addc_co_u32_e32 v11, vcc, 0, v15, vcc
	global_load_dword v19, v[10:11], off offset:32
	s_nop 0
	global_load_dwordx2 v[10:11], v[2:3], off
	global_load_dwordx2 v[12:13], v[4:5], off
	v_add_co_u32_e32 v16, vcc, s44, v14
	s_lshl_b64 s[6:7], s[6:7], 11
	s_nop 0
	v_addc_co_u32_e32 v17, vcc, 0, v15, vcc
	v_add_co_u32_e32 v174, vcc, 0x2000, v14
	s_nop 1
	v_addc_co_u32_e32 v175, vcc, 0, v15, vcc
	global_load_dword v170, v[174:175], off offset:1568
	v_add_co_u32_e32 v174, vcc, 0x3000, v14
	s_nop 1
	v_addc_co_u32_e32 v175, vcc, 0, v15, vcc
	global_load_dword v171, v[174:175], off offset:3104
	v_add_co_u32_e32 v174, vcc, 0x5000, v14
	s_nop 1
	v_addc_co_u32_e32 v175, vcc, 0, v15, vcc
	global_load_dword v172, v[174:175], off offset:544
	s_lshl_b64 s[30:31], s[30:31], 11
	s_add_i32 s49, s49, s96
	s_cmpk_gt_i32 s49, 0x1ff
	s_waitcnt vmcnt(0)
	v_lshlrev_b32_e32 v18, 16, v19
	v_and_b32_e32 v19, 0xffff0000, v19
	v_add_f32_e32 v20, v19, v18
	ds_bpermute_b32 v21, v24, v20
	s_waitcnt lgkmcnt(0)
	v_add_f32_e32 v20, v20, v21
	ds_bpermute_b32 v21, v25, v20
	s_waitcnt lgkmcnt(0)
	v_add_f32_e32 v20, v20, v21
	ds_bpermute_b32 v21, v26, v20
	s_waitcnt lgkmcnt(0)
	v_add_f32_e32 v20, v20, v21
	ds_bpermute_b32 v21, v27, v20
	s_waitcnt lgkmcnt(0)
	v_add_f32_e32 v20, v20, v21
	ds_bpermute_b32 v21, v28, v20
	s_waitcnt lgkmcnt(0)
	v_add_f32_e32 v20, v20, v21
	ds_bpermute_b32 v21, v29, v20
	s_waitcnt lgkmcnt(0)
	v_add_f32_e32 v20, v20, v21
	v_mul_f32_e32 v20, 0x3c000000, v20
	v_pk_add_f32 v[18:19], v[18:19], v[20:21] op_sel_hi:[1,0] neg_lo:[0,1] neg_hi:[0,1]
	s_nop 0
	v_pk_mul_f32 v[20:21], v[18:19], v[18:19]
	s_nop 0
	v_add_f32_e32 v20, v20, v21
	ds_bpermute_b32 v21, v24, v20
	s_waitcnt lgkmcnt(0)
	v_add_f32_e32 v20, v20, v21
	ds_bpermute_b32 v21, v25, v20
	s_waitcnt lgkmcnt(0)
	v_add_f32_e32 v20, v20, v21
	ds_bpermute_b32 v21, v26, v20
	s_waitcnt lgkmcnt(0)
	v_add_f32_e32 v20, v20, v21
	ds_bpermute_b32 v21, v27, v20
	s_waitcnt lgkmcnt(0)
	v_add_f32_e32 v20, v20, v21
	ds_bpermute_b32 v21, v28, v20
	s_waitcnt lgkmcnt(0)
	v_add_f32_e32 v20, v20, v21
	ds_bpermute_b32 v21, v29, v20
	s_waitcnt lgkmcnt(0)
	v_add_f32_e32 v20, v20, v21
	v_fmamk_f32 v20, v20, 0x3c000000, v30
	v_mul_f32_e32 v21, 0x4b800000, v20
	v_cmp_gt_f32_e32 vcc, s35, v20
	s_nop 1
	v_cndmask_b32_e32 v20, v20, v21, vcc
	v_rsq_f32_e32 v20, v20
	s_nop 0
	v_mul_f32_e32 v21, 0x45800000, v20
	v_cndmask_b32_e32 v20, v20, v21, vcc
	v_pk_mul_f32 v[18:19], v[18:19], v[20:21] op_sel_hi:[1,0]
	v_add_co_u32_e32 v22, vcc, s45, v14
	v_pk_fma_f32 v[18:19], v[10:11], v[18:19], v[12:13]
	global_store_dwordx2 v[52:53], v[18:19], off
	s_nop 0
	v_addc_co_u32_e32 v23, vcc, 0, v15, vcc
	s_nop 0
	v_lshlrev_b32_e32 v20, 16, v170
	v_and_b32_e32 v21, 0xffff0000, v170
	v_add_f32_e32 v31, v21, v20
	ds_bpermute_b32 v54, v24, v31
	s_waitcnt lgkmcnt(0)
	v_add_f32_e32 v31, v31, v54
	ds_bpermute_b32 v54, v25, v31
	s_waitcnt lgkmcnt(0)
	v_add_f32_e32 v31, v31, v54
	ds_bpermute_b32 v54, v26, v31
	s_waitcnt lgkmcnt(0)
	v_add_f32_e32 v31, v31, v54
	ds_bpermute_b32 v54, v27, v31
	s_waitcnt lgkmcnt(0)
	v_add_f32_e32 v31, v31, v54
	ds_bpermute_b32 v54, v28, v31
	s_waitcnt lgkmcnt(0)
	v_add_f32_e32 v31, v31, v54
	ds_bpermute_b32 v54, v29, v31
	s_waitcnt lgkmcnt(0)
	v_add_f32_e32 v31, v31, v54
	v_mul_f32_e32 v54, 0x3c000000, v31
	v_pk_add_f32 v[20:21], v[20:21], v[54:55] op_sel_hi:[1,0] neg_lo:[0,1] neg_hi:[0,1]
	s_nop 0
	v_pk_mul_f32 v[54:55], v[20:21], v[20:21]
	s_nop 0
	v_add_f32_e32 v31, v54, v55
	ds_bpermute_b32 v54, v24, v31
	s_waitcnt lgkmcnt(0)
	v_add_f32_e32 v31, v31, v54
	ds_bpermute_b32 v54, v25, v31
	s_waitcnt lgkmcnt(0)
	v_add_f32_e32 v31, v31, v54
	ds_bpermute_b32 v54, v26, v31
	s_waitcnt lgkmcnt(0)
	v_add_f32_e32 v31, v31, v54
	ds_bpermute_b32 v54, v27, v31
	s_waitcnt lgkmcnt(0)
	v_add_f32_e32 v31, v31, v54
	ds_bpermute_b32 v54, v28, v31
	s_waitcnt lgkmcnt(0)
	v_add_f32_e32 v31, v31, v54
	ds_bpermute_b32 v54, v29, v31
	s_waitcnt lgkmcnt(0)
	v_add_f32_e32 v31, v31, v54
	v_fmamk_f32 v31, v31, 0x3c000000, v30
	v_mul_f32_e32 v54, 0x4b800000, v31
	v_cmp_gt_f32_e32 vcc, s35, v31
	s_nop 1
	v_cndmask_b32_e32 v31, v31, v54, vcc
	v_rsq_f32_e32 v31, v31
	s_nop 0
	v_mul_f32_e32 v54, 0x45800000, v31
	v_cndmask_b32_e32 v54, v31, v54, vcc
	v_pk_mul_f32 v[20:21], v[20:21], v[54:55] op_sel_hi:[1,0]
	s_nop 0
	v_pk_fma_f32 v[20:21], v[10:11], v[20:21], v[12:13]
	global_store_dwordx2 v[52:53], v[20:21], off offset:2048
	s_nop 0
	v_add_co_u32_e32 v52, vcc, s3, v52
	s_nop 0
	v_lshlrev_b32_e32 v56, 16, v171
	v_and_b32_e32 v57, 0xffff0000, v171
	v_add_f32_e32 v31, v57, v56
	ds_bpermute_b32 v58, v24, v31
	v_addc_co_u32_e32 v53, vcc, 0, v53, vcc
	v_add_co_u32_e32 v54, vcc, s46, v14
	s_waitcnt lgkmcnt(0)
	v_add_f32_e32 v31, v31, v58
	ds_bpermute_b32 v58, v25, v31
	v_addc_co_u32_e32 v55, vcc, 0, v15, vcc
	s_waitcnt lgkmcnt(0)
	v_add_f32_e32 v31, v31, v58
	ds_bpermute_b32 v58, v26, v31
	s_waitcnt lgkmcnt(0)
	v_add_f32_e32 v31, v31, v58
	ds_bpermute_b32 v58, v27, v31
	s_waitcnt lgkmcnt(0)
; __device__ __forceinline__ float bf2f(unsigned b) { return __uint_as_float(b << 16); }
; __device__ __forceinline__ unsigned pk2(float lo, float hi) { unsigned r; asm("v_cvt_pk_bf16_f32 %0, %1, %2" : "=v"(r) : "v"(lo), "v"(hi)); return r; }
; __device__ __forceinline__ void sgu_sample_item(int item, const u16* PROJ, u16* MIXIN, const float* gln, const float* bln, const float* wsp, const float* bsp, float* vout, int lane) {
;     ...
;     for (int t = 0; t < 4; ++t) { const size_t row = (size_t)TP + n * 4 + t; const unsigned raw = *(const unsigned*)(PROJ + row * NPROJ + C_VS + c0);
;         const float x0 = bf2f(raw & 0xffffu), x1 = bf2f(raw >> 16);
;         const float mu = wave_sum(x0 + x1) * (1.f / 128.f), d0 = x0 - mu, d1 = x1 - mu;
;         const float rstd = rsqrtf(wave_sum(d0 * d0 + d1 * d1) * (1.f / 128.f) + EPS);
;         vn0[t] = d0 * rstd * g0 + b0; vn1[t] = d1 * rstd * g1 + b1;
;         *(f32x2*)(vout + ((size_t)n * 4 + t) * 512 + c0) = (f32x2){vn0[t], vn1[t]}; }
; #pragma unroll
;     for (int t = 0; t < 4; ++t) { const size_t row = (size_t)TP + n * 4 + t; float m0 = bsp[hh * 128 + t], m1 = m0;
; #pragma unroll
;         for (int s = 0; s < 4; ++s) if (s <= t) { const float wv = wsp[((size_t)hh * 128 + t) * 128 + s]; m0 += wv * vn0[s]; m1 += wv * vn1[s]; }
;         const unsigned uw = *(const unsigned*)(PROJ + row * NPROJ + C_U + c0);
;         *(unsigned*)(MIXIN + row * D + 512 + c0) = pk2(bf2f(uw & 0xffffu) * m0, bf2f(uw >> 16) * m1); }
	v_add_f32_e32 v31, v31, v58
	ds_bpermute_b32 v58, v28, v31
	s_waitcnt lgkmcnt(0)
	v_add_f32_e32 v31, v31, v58
	ds_bpermute_b32 v58, v29, v31
	s_waitcnt lgkmcnt(0)
	v_add_f32_e32 v31, v31, v58
	v_mul_f32_e32 v58, 0x3c000000, v31
	v_pk_add_f32 v[56:57], v[56:57], v[58:59] op_sel_hi:[1,0] neg_lo:[0,1] neg_hi:[0,1]
	s_nop 0
	v_pk_mul_f32 v[58:59], v[56:57], v[56:57]
	s_nop 0
	v_add_f32_e32 v31, v58, v59
	ds_bpermute_b32 v58, v24, v31
	s_waitcnt lgkmcnt(0)
	v_add_f32_e32 v31, v31, v58
	ds_bpermute_b32 v58, v25, v31
	s_waitcnt lgkmcnt(0)
	v_add_f32_e32 v31, v31, v58
	ds_bpermute_b32 v58, v26, v31
	s_waitcnt lgkmcnt(0)
	v_add_f32_e32 v31, v31, v58
	ds_bpermute_b32 v58, v27, v31
	s_waitcnt lgkmcnt(0)
	v_add_f32_e32 v31, v31, v58
	ds_bpermute_b32 v58, v28, v31
	s_waitcnt lgkmcnt(0)
	v_add_f32_e32 v31, v31, v58
	ds_bpermute_b32 v58, v29, v31
	s_waitcnt lgkmcnt(0)
	v_add_f32_e32 v31, v31, v58
	v_fmamk_f32 v31, v31, 0x3c000000, v30
	v_mul_f32_e32 v58, 0x4b800000, v31
	v_cmp_gt_f32_e32 vcc, s35, v31
	s_nop 1
	v_cndmask_b32_e32 v31, v31, v58, vcc
	v_rsq_f32_e32 v31, v31
	s_nop 0
	v_mul_f32_e32 v58, 0x45800000, v31
	v_cndmask_b32_e32 v58, v31, v58, vcc
	v_pk_mul_f32 v[56:57], v[56:57], v[58:59] op_sel_hi:[1,0]
	v_lshl_add_u64 v[58:59], v[8:9], 0, s[6:7]
	v_pk_fma_f32 v[56:57], v[10:11], v[56:57], v[12:13]
	global_store_dwordx2 v[52:53], v[56:57], off
	s_nop 0
	v_add_co_u32_e32 v62, vcc, s48, v58
	s_mov_b64 s[6:7], vcc
	v_add_co_u32_e32 v66, vcc, 0x4000, v14
	s_nop 0
	v_lshlrev_b32_e32 v14, 16, v172
	v_addc_co_u32_e32 v67, vcc, 0, v15, vcc
	v_and_b32_e32 v15, 0xffff0000, v172
	v_add_f32_e32 v31, v15, v14
	ds_bpermute_b32 v54, v24, v31
	s_waitcnt lgkmcnt(0)
	v_add_f32_e32 v31, v31, v54
	ds_bpermute_b32 v54, v25, v31
	s_waitcnt lgkmcnt(0)
	v_add_f32_e32 v31, v31, v54
	ds_bpermute_b32 v54, v26, v31
	s_waitcnt lgkmcnt(0)
	v_add_f32_e32 v31, v31, v54
	ds_bpermute_b32 v54, v27, v31
	s_waitcnt lgkmcnt(0)
	v_add_f32_e32 v31, v31, v54
	ds_bpermute_b32 v54, v28, v31
	s_waitcnt lgkmcnt(0)
	v_add_f32_e32 v31, v31, v54
	ds_bpermute_b32 v54, v29, v31
	s_waitcnt lgkmcnt(0)
	v_add_f32_e32 v31, v31, v54
	v_mul_f32_e32 v54, 0x3c000000, v31
	v_pk_add_f32 v[14:15], v[14:15], v[54:55] op_sel_hi:[1,0] neg_lo:[0,1] neg_hi:[0,1]
	s_nop 0
	v_pk_mul_f32 v[54:55], v[14:15], v[14:15]
	s_nop 0
	v_add_f32_e32 v31, v54, v55
	ds_bpermute_b32 v54, v24, v31
	s_waitcnt lgkmcnt(0)
	v_add_f32_e32 v31, v31, v54
	ds_bpermute_b32 v54, v25, v31
	s_waitcnt lgkmcnt(0)
	v_add_f32_e32 v31, v31, v54
	ds_bpermute_b32 v54, v26, v31
	s_waitcnt lgkmcnt(0)
	v_add_f32_e32 v31, v31, v54
	ds_bpermute_b32 v54, v27, v31
	s_waitcnt lgkmcnt(0)
	v_add_f32_e32 v31, v31, v54
	ds_bpermute_b32 v54, v28, v31
	s_waitcnt lgkmcnt(0)
	v_add_f32_e32 v31, v31, v54
	ds_bpermute_b32 v54, v29, v31
	s_waitcnt lgkmcnt(0)
	v_add_f32_e32 v31, v31, v54
	v_fmamk_f32 v31, v31, 0x3c000000, v30
	v_mul_f32_e32 v54, 0x4b800000, v31
	v_cmp_gt_f32_e32 vcc, s35, v31
	s_nop 1
	v_cndmask_b32_e32 v31, v31, v54, vcc
	v_rsq_f32_e32 v31, v31
	s_nop 0
	v_mul_f32_e32 v54, 0x45800000, v31
	v_cndmask_b32_e32 v54, v31, v54, vcc
	v_pk_mul_f32 v[14:15], v[14:15], v[54:55] op_sel_hi:[1,0]
	s_nop 0
	v_pk_fma_f32 v[68:69], v[10:11], v[14:15], v[12:13]
	global_store_dwordx2 v[52:53], v[68:69], off offset:2048
	global_load_dwordx4 v[10:13], v1, s[8:9]
	global_load_dword v31, v1, s[20:21]
	global_load_dword v55, v0, s[42:43] offset:3104
	global_load_dwordx2 v[70:71], v1, s[20:21] offset:512
	global_load_dword v60, v[16:17], off offset:544
	global_load_dwordx3 v[52:54], v1, s[20:21] offset:1024
	global_load_dword v64, v[22:23], off offset:2080
	s_nop 0
	global_load_dwordx4 v[14:17], v1, s[20:21] offset:1536
	global_load_dword v72, v[66:67], off offset:3616
	v_add_co_u32_e32 v66, vcc, s47, v58
	v_lshl_add_u64 v[22:23], v[8:9], 0, s[30:31]
	s_nop 0
	v_addc_co_u32_e32 v67, vcc, 0, v59, vcc
	v_addc_co_u32_e64 v63, vcc, 0, v59, s[6:7]
	s_waitcnt vmcnt(7)
	v_fma_f32 v58, v18, v31, v10
	v_fma_f32 v10, v19, v31, v10
	s_waitcnt vmcnt(6)
	v_lshlrev_b32_e32 v31, 16, v55
	v_and_b32_e32 v55, 0xffff0000, v55
	s_waitcnt vmcnt(5)
	v_fma_f32 v59, v18, v70, v11
	v_fma_f32 v11, v19, v70, v11
	s_waitcnt vmcnt(3)
	v_fma_f32 v73, v18, v52, v12
	v_fma_f32 v12, v19, v52, v12
	s_waitcnt vmcnt(1)
	v_fma_f32 v19, v19, v14, v13
	v_fmac_f32_e32 v13, v18, v14
	v_mul_f32_e32 v10, v10, v55
	v_lshlrev_b32_e32 v70, 16, v60
	v_and_b32_e32 v60, 0xffff0000, v60
	v_mul_f32_e32 v31, v58, v31
	v_fmac_f32_e32 v59, v20, v71
	v_fmac_f32_e32 v11, v21, v71
	v_fmac_f32_e32 v73, v20, v53
	v_fmac_f32_e32 v12, v21, v53
	v_fmac_f32_e32 v19, v21, v15
	v_fmac_f32_e32 v13, v20, v15
	v_cvt_pk_bf16_f32 v10, v31, v10
	v_lshlrev_b32_e32 v52, 16, v64
	v_and_b32_e32 v64, 0xffff0000, v64
	v_mul_f32_e32 v15, v59, v70
	v_mul_f32_e32 v11, v11, v60
	v_fmac_f32_e32 v73, v56, v54
	v_fmac_f32_e32 v12, v57, v54
	v_fmac_f32_e32 v19, v57, v16
	v_fmac_f32_e32 v13, v56, v16
	global_store_dword v[22:23], v10, off offset:1024
	v_cvt_pk_bf16_f32 v10, v15, v11
	s_waitcnt vmcnt(1)
	v_lshlrev_b32_e32 v14, 16, v72
	v_and_b32_e32 v18, 0xffff0000, v72
	v_mul_f32_e32 v11, v73, v52
	v_mul_f32_e32 v12, v12, v64
	v_fmac_f32_e32 v19, v69, v17
	v_fmac_f32_e32 v13, v68, v17
	global_store_dword v[66:67], v10, off offset:3072
	v_cvt_pk_bf16_f32 v10, v11, v12
	v_mul_f32_e32 v11, v13, v14
	v_mul_f32_e32 v12, v19, v18
	global_store_dword v[62:63], v10, off offset:1024
	v_cvt_pk_bf16_f32 v10, v11, v12
	global_store_dword v[62:63], v10, off offset:3072
	s_cbranch_scc0 .LBB0_250

; #define LAS __attribute__((address_space(3)))
; __device__ __forceinline__ unsigned pk2(float lo, float hi) { unsigned r; asm("v_cvt_pk_bf16_f32 %0, %1, %2" : "=v"(r) : "v"(lo), "v"(hi)); return r; }
; __device__ __forceinline__ void transpose_tile(const float* W, int K, int N, u16* WT, int k0, int n0, LAS float* scr, int tid) {
; #pragma unroll
;     for (int i = 0; i < 8; ++i) { const int k = i * 8 + (tid >> 6), n = tid & 63; scr[k * 65 + n] = (n0 + n < N) ? W[(size_t)(k0 + k) * N + n0 + n] : 0.f; }
;     __syncthreads();
;     const int n = tid >> 3, c = tid & 7; const LAS float* s = scr + (8 * c) * 65 + n;
;     u32x4 o; o.x = pk2(s[0], s[65]); o.y = pk2(s[130], s[195]); o.z = pk2(s[260], s[325]); o.w = pk2(s[390], s[455]);
;     *(u32x4*)(WT + (size_t)(n0 + n) * K + k0 + 8 * c) = o;
;     __syncthreads();
; }
; __global__ void __launch_bounds__(512, 2) fwd_kernel(Args args) {
;     ...
;         { const int f = (G > 32) ? 32 : 0, rk = bid - f, ni = G - f; LAS float* scr = (LAS float*)lds;
;           if (rk >= 0) for (int r = rk; r < 16 * 88; r += ni) transpose_tile(args.in[I_WUP], D, FF2, WupT, (r / 88) * 64, (r % 88) * 64, scr, tid); }
.LBB0_463:
	s_cmp_gt_i32 s14, 32
	s_cselect_b32 s12, 0xffffffe0, 0
	s_add_i32 s3, s12, s2
	s_cmpk_gt_u32 s3, 0x57f
	s_cbranch_scc1 .LBB0_474
	s_add_i32 s12, s12, s14
	s_waitcnt lgkmcnt(0)
	s_mov_b64 s[8:9], s[40:41]
	v_lshrrev_b32_e32 v2, 6, v129
	v_lshrrev_b32_e32 v3, 4, v128
	v_readfirstlane_b32 s20, v2
	v_and_b32_e32 v4, 15, v128
	v_mul_u32_u24_e32 v0, 0x16000, v3
	v_lshl_add_u32 v0, v4, 4, v0
	v_mul_u32_u24_e32 v1, 0x2000, v4
	v_lshl_add_u32 v1, v3, 3, v1
	s_lshr_b32 s13, s20, 2
	s_and_b32 s20, s20, 3
	s_mul_i32 s0, s13, s12
	s_add_i32 s3, s3, s0
	s_lshl_b32 s12, s12, 1
.Ltr3_loop:
	s_cmpk_lt_u32 s3, 0x580
	s_cbranch_scc0 .LBB0_474
	s_mul_hi_u32 s1, s3, 0x2e8ba2e9
	s_lshr_b32 s1, s1, 4
	s_mul_i32 s30, s1, 88
	s_sub_i32 s0, s3, s30
	s_lshl_b32 s30, s1, 6
	s_lshl_b32 s10, s20, 4
	s_add_i32 s30, s30, s10
	s_mul_i32 s30, s30, 0x5800
	s_lshl_b32 s10, s0, 8
	s_add_i32 s30, s30, s10
	s_add_u32 s10, s8, s30
	s_addc_u32 s11, s9, 0
	global_load_dwordx4 v[24:27], v0, s[10:11]
	s_add_u32 s10, s10, 0x5800
	s_addc_u32 s11, s11, 0
	global_load_dwordx4 v[28:31], v0, s[10:11]
	s_add_u32 s10, s10, 0x5800
	s_addc_u32 s11, s11, 0
	global_load_dwordx4 v[32:35], v0, s[10:11]
	s_add_u32 s10, s10, 0x5800
	s_addc_u32 s11, s11, 0
	global_load_dwordx4 v[36:39], v0, s[10:11]
	s_add_i32 s21, s3, s12
	s_cmpk_lt_u32 s21, 0x580
	s_cselect_b32 s21, s21, s3
	s_mul_hi_u32 s1, s21, 0x2e8ba2e9
	s_lshr_b32 s1, s1, 4
	s_mul_i32 s30, s1, 88
	s_sub_i32 s0, s21, s30
	s_lshl_b32 s30, s1, 6
	s_lshl_b32 s10, s20, 4
	s_add_i32 s30, s30, s10
	s_mul_i32 s30, s30, 0x5800
	s_lshl_b32 s10, s0, 8
	s_add_i32 s30, s30, s10
	s_add_u32 s10, s8, s30
	s_addc_u32 s11, s9, 0
	global_load_dwordx4 v[40:43], v0, s[10:11]
	s_add_u32 s10, s10, 0x5800
	s_addc_u32 s11, s11, 0
	global_load_dwordx4 v[44:47], v0, s[10:11]
	s_add_u32 s10, s10, 0x5800
	s_addc_u32 s11, s11, 0
	global_load_dwordx4 v[48:51], v0, s[10:11]
	s_add_u32 s10, s10, 0x5800
	s_addc_u32 s11, s11, 0
	global_load_dwordx4 v[52:55], v0, s[10:11]
	s_mul_hi_u32 s1, s3, 0x2e8ba2e9
	s_lshr_b32 s1, s1, 4
	s_mul_i32 s30, s1, 88
	s_sub_i32 s0, s3, s30
	s_lshl_b32 s30, s0, 17
	s_lshl_b32 s1, s1, 7
	s_add_i32 s30, s30, s1
	s_lshl_b32 s1, s20, 5
	s_add_i32 s30, s30, s1
	s_add_u32 s10, s54, s30
	s_addc_u32 s11, s55, 0
	s_waitcnt vmcnt(4)
	v_cvt_pk_bf16_f32 v56, v24, v28
	v_cvt_pk_bf16_f32 v57, v32, v36
	v_cvt_pk_bf16_f32 v58, v25, v29
	v_cvt_pk_bf16_f32 v59, v33, v37
	v_cvt_pk_bf16_f32 v60, v26, v30
	v_cvt_pk_bf16_f32 v61, v34, v38
	v_cvt_pk_bf16_f32 v62, v27, v31
	v_cvt_pk_bf16_f32 v63, v35, v39
	global_store_dwordx2 v1, v[56:57], s[10:11]
	s_add_u32 s10, s10, 0x800
	s_addc_u32 s11, s11, 0
	global_store_dwordx2 v1, v[58:59], s[10:11]
	s_add_u32 s10, s10, 0x800
	s_addc_u32 s11, s11, 0
	global_store_dwordx2 v1, v[60:61], s[10:11]
	s_add_u32 s10, s10, 0x800
	s_addc_u32 s11, s11, 0
	global_store_dwordx2 v1, v[62:63], s[10:11]
	s_cmp_eq_u32 s21, s3
	s_cbranch_scc1 .LBB0_474
	s_mul_hi_u32 s1, s21, 0x2e8ba2e9
	s_lshr_b32 s1, s1, 4
	s_mul_i32 s30, s1, 88
	s_sub_i32 s0, s21, s30
	s_lshl_b32 s30, s0, 17
	s_lshl_b32 s1, s1, 7
	s_add_i32 s30, s30, s1
	s_lshl_b32 s1, s20, 5
	s_add_i32 s30, s30, s1
	s_add_u32 s10, s54, s30
	s_addc_u32 s11, s55, 0
	s_waitcnt vmcnt(4)
	v_cvt_pk_bf16_f32 v64, v40, v44
	v_cvt_pk_bf16_f32 v65, v48, v52
	v_cvt_pk_bf16_f32 v66, v41, v45
	v_cvt_pk_bf16_f32 v67, v49, v53
	v_cvt_pk_bf16_f32 v68, v42, v46
	v_cvt_pk_bf16_f32 v69, v50, v54
	v_cvt_pk_bf16_f32 v70, v43, v47
	v_cvt_pk_bf16_f32 v71, v51, v55
	global_store_dwordx2 v1, v[64:65], s[10:11]
	s_add_u32 s10, s10, 0x800
	s_addc_u32 s11, s11, 0
	global_store_dwordx2 v1, v[66:67], s[10:11]
	s_add_u32 s10, s10, 0x800
	s_addc_u32 s11, s11, 0
	global_store_dwordx2 v1, v[68:69], s[10:11]
	s_add_u32 s10, s10, 0x800
	s_addc_u32 s11, s11, 0
	global_store_dwordx2 v1, v[70:71], s[10:11]
	s_add_i32 s3, s21, s12
	s_branch .Ltr3_loop

; __device__ __forceinline__ unsigned pk2(float lo, float hi) { unsigned r; asm("v_cvt_pk_bf16_f32 %0, %1, %2" : "=v"(r) : "v"(lo), "v"(hi)); return r; }
; __global__ void __launch_bounds__(512, 2) fwd_kernel(Args args) {
;     ...
;         for (int m = gw; m < T; m += NGW) {
;             const float* pp = (m < TP) ? args.in[I_PP] + (size_t)m * PLE : args.in[I_PS] + (size_t)(m - TP) * PLE;
;             const f32x4 v = ((const f32x4*)pp)[lane]; u32x2 wv; wv.x = pk2(v.x, v.y); wv.y = pk2(v.z, v.w); ((u32x2*)(PB + (size_t)m * PLE))[lane] = wv; }
.LBB0_819:
	s_andn2_b64 vcc, exec, s[30:31]
	s_cbranch_vccnz .LBB0_824
	s_ashr_i32 s35, s34, 31
	s_ashr_i32 s97, s96, 31
	s_lshl_b64 s[0:1], s[34:35], 10
	v_mov_b32_e32 v135, 0
	s_add_u32 s0, s24, s0
	v_lshl_add_u64 v[0:1], s[12:13], 0, v[134:135]
	s_addc_u32 s1, s25, s1
	s_lshl_b64 s[6:7], s[96:97], 10
	s_mov_b32 s19, 0
	v_lshlrev_b32_e32 v2, 4, v128
	s_mov_b64 s[22:23], s[34:35]
	s_cmp_lg_u32 s96, 0x800
	s_cbranch_scc1 .LBB0_822
	global_load_dwordx4 v[4:7], v2, s[0:1]
	s_add_u32 s0, s0, s6
	s_addc_u32 s1, s1, s7
	global_load_dwordx4 v[8:11], v2, s[0:1]
	s_add_u32 s0, s0, s6
	s_addc_u32 s1, s1, s7
	global_load_dwordx4 v[12:15], v2, s[0:1]
	s_add_u32 s0, s0, s6
	s_addc_u32 s1, s1, s7
	global_load_dwordx4 v[16:19], v2, s[0:1]
	s_add_u32 s0, s0, s6
	s_addc_u32 s1, s1, s7
	global_load_dwordx4 v[20:23], v2, s[0:1]
	s_add_u32 s0, s0, s6
	s_addc_u32 s1, s1, s7
	global_load_dwordx4 v[24:27], v2, s[0:1]
	s_add_u32 s0, s0, s6
	s_addc_u32 s1, s1, s7
	global_load_dwordx4 v[28:31], v2, s[0:1]
	s_add_u32 s0, s0, s6
	s_addc_u32 s1, s1, s7
	global_load_dwordx4 v[32:35], v2, s[0:1]
	s_lshl_b64 s[24:25], s[34:35], 10
	s_add_u32 s36, s26, s24
	s_addc_u32 s37, s27, s25
	s_cmpk_lt_i32 s34, 0x200
	s_cselect_b32 s36, s36, s0
	s_cselect_b32 s37, s37, s1
	global_load_dwordx4 v[36:39], v2, s[36:37]
	s_lshl_b64 s[24:25], s[34:35], 9
	s_mov_b32 s22, 0x100000
	s_mov_b32 s23, 0
	v_lshl_add_u64 v[0:1], v[0:1], 0, s[24:25]
	s_waitcnt vmcnt(8)
	v_cvt_pk_bf16_f32 v4, v4, v5
	v_cvt_pk_bf16_f32 v5, v6, v7
	global_store_dwordx2 v[0:1], v[4:5], off
	v_lshl_add_u64 v[0:1], v[0:1], 0, s[22:23]
	s_waitcnt vmcnt(8)
	v_cvt_pk_bf16_f32 v8, v8, v9
	v_cvt_pk_bf16_f32 v9, v10, v11
	global_store_dwordx2 v[0:1], v[8:9], off
	v_lshl_add_u64 v[0:1], v[0:1], 0, s[22:23]
	s_waitcnt vmcnt(8)
	v_cvt_pk_bf16_f32 v12, v12, v13
	v_cvt_pk_bf16_f32 v13, v14, v15
	global_store_dwordx2 v[0:1], v[12:13], off
	v_lshl_add_u64 v[0:1], v[0:1], 0, s[22:23]
	s_waitcnt vmcnt(8)
	v_cvt_pk_bf16_f32 v16, v16, v17
	v_cvt_pk_bf16_f32 v17, v18, v19
	global_store_dwordx2 v[0:1], v[16:17], off
	v_lshl_add_u64 v[0:1], v[0:1], 0, s[22:23]
	s_waitcnt vmcnt(8)
	v_cvt_pk_bf16_f32 v20, v20, v21
	v_cvt_pk_bf16_f32 v21, v22, v23
	global_store_dwordx2 v[0:1], v[20:21], off
	v_lshl_add_u64 v[0:1], v[0:1], 0, s[22:23]
	s_waitcnt vmcnt(8)
	v_cvt_pk_bf16_f32 v24, v24, v25
	v_cvt_pk_bf16_f32 v25, v26, v27
	global_store_dwordx2 v[0:1], v[24:25], off
	v_lshl_add_u64 v[0:1], v[0:1], 0, s[22:23]
	s_waitcnt vmcnt(8)
	v_cvt_pk_bf16_f32 v28, v28, v29
	v_cvt_pk_bf16_f32 v29, v30, v31
	global_store_dwordx2 v[0:1], v[28:29], off
	v_lshl_add_u64 v[0:1], v[0:1], 0, s[22:23]
	s_waitcnt vmcnt(8)
	v_cvt_pk_bf16_f32 v32, v32, v33
	v_cvt_pk_bf16_f32 v33, v34, v35
	global_store_dwordx2 v[0:1], v[32:33], off
	v_lshl_add_u64 v[0:1], v[0:1], 0, s[22:23]
	s_cmpk_lt_i32 s34, 0x200
	s_cbranch_scc0 .Lpb_done
	s_waitcnt vmcnt(8)
	v_cvt_pk_bf16_f32 v36, v36, v37
	v_cvt_pk_bf16_f32 v37, v38, v39
	global_store_dwordx2 v[0:1], v[36:37], off
.Lpb_done:
	s_branch .LBB0_824
	s_branch .LBB0_822
